# nt hint on the final f32 output stores (layer-1 out-proj epilogue; never re-read)
# speedup vs baseline: 1.0317x; 1.0030x over previous
.LBB0_878:
	v_readlane_b32 vcc_lo, v253, 47
	v_readlane_b32 vcc_hi, v253, 48
	s_nop 1
	s_and_b64 vcc, exec, vcc
	s_cbranch_scc0 .Lof0_h
	v_lshrrev_b32_e32 v112, 6, v250
	v_mul_u32_u24_e32 v112, 0x2200, v112
	v_lshrrev_b32_e32 v113, 4, v225
	v_mul_u32_u24_e32 v113, 0x110, v113
	v_and_b32_e32 v114, 15, v225
	v_lshl_add_u32 v113, v114, 4, v113
	v_add_u32_e32 v112, v112, v113
	v_add_u32_e32 v112, 0x1000, v112
	ds_read_b128 v[96:99], v112
	ds_read_b128 v[100:103], v112 offset:1088
	ds_read_b128 v[104:107], v112 offset:2176
	ds_read_b128 v[108:111], v112 offset:3264
	s_waitcnt lgkmcnt(3)
	global_store_dwordx4 v169, v[96:99], s[100:101] nt
	s_add_u32 s100, s100, 0x4000
	s_addc_u32 s101, s101, 0
	s_waitcnt lgkmcnt(2)
	global_store_dwordx4 v169, v[100:103], s[100:101] nt
	s_add_u32 s100, s100, 0x4000
	s_addc_u32 s101, s101, 0
	s_waitcnt lgkmcnt(1)
	global_store_dwordx4 v169, v[104:107], s[100:101] nt
	s_add_u32 s100, s100, 0x4000
	s_addc_u32 s101, s101, 0
	s_waitcnt lgkmcnt(0)
	global_store_dwordx4 v169, v[108:111], s[100:101] nt
	s_add_u32 s100, s100, 0x4000
	s_addc_u32 s101, s101, 0
	ds_read_b128 v[96:99], v112 offset:4352
	ds_read_b128 v[100:103], v112 offset:5440
	ds_read_b128 v[104:107], v112 offset:6528
	ds_read_b128 v[108:111], v112 offset:7616
	s_waitcnt lgkmcnt(3)
	global_store_dwordx4 v169, v[96:99], s[100:101] nt
	s_add_u32 s100, s100, 0x4000
	s_addc_u32 s101, s101, 0
	s_waitcnt lgkmcnt(2)
	global_store_dwordx4 v169, v[100:103], s[100:101] nt
	s_add_u32 s100, s100, 0x4000
	s_addc_u32 s101, s101, 0
	s_waitcnt lgkmcnt(1)
	global_store_dwordx4 v169, v[104:107], s[100:101] nt
	s_add_u32 s100, s100, 0x4000
	s_addc_u32 s101, s101, 0
	s_waitcnt lgkmcnt(0)
	global_store_dwordx4 v169, v[108:111], s[100:101] nt
	s_add_u32 s100, s100, 0x4000
	s_addc_u32 s101, s101, 0
	s_branch .Lof0_d

.LBB0_910:
	v_readlane_b32 vcc_lo, v253, 47
	v_readlane_b32 vcc_hi, v253, 48
	s_nop 1
	s_and_b64 vcc, exec, vcc
	s_cbranch_scc0 .Lof1_h
	v_lshrrev_b32_e32 v80, 6, v250
	v_mul_u32_u24_e32 v80, 0x2200, v80
	v_lshrrev_b32_e32 v81, 4, v225
	v_mul_u32_u24_e32 v81, 0x110, v81
	v_and_b32_e32 v82, 15, v225
	v_lshl_add_u32 v81, v82, 4, v81
	v_add_u32_e32 v80, v80, v81
	v_add_u32_e32 v80, 0x1000, v80
	ds_read_b128 v[64:67], v80
	ds_read_b128 v[68:71], v80 offset:1088
	ds_read_b128 v[72:75], v80 offset:2176
	ds_read_b128 v[76:79], v80 offset:3264
	s_waitcnt lgkmcnt(3)
	global_store_dwordx4 v169, v[64:67], s[100:101] nt
	s_add_u32 s100, s100, 0x4000
	s_addc_u32 s101, s101, 0
	s_waitcnt lgkmcnt(2)
	global_store_dwordx4 v169, v[68:71], s[100:101] nt
	s_add_u32 s100, s100, 0x4000
	s_addc_u32 s101, s101, 0
	s_waitcnt lgkmcnt(1)
	global_store_dwordx4 v169, v[72:75], s[100:101] nt
	s_add_u32 s100, s100, 0x4000
	s_addc_u32 s101, s101, 0
	s_waitcnt lgkmcnt(0)
	global_store_dwordx4 v169, v[76:79], s[100:101] nt
	s_add_u32 s100, s100, 0x4000
	s_addc_u32 s101, s101, 0
	ds_read_b128 v[64:67], v80 offset:4352
	ds_read_b128 v[68:71], v80 offset:5440
	ds_read_b128 v[72:75], v80 offset:6528
	ds_read_b128 v[76:79], v80 offset:7616
	s_waitcnt lgkmcnt(3)
	global_store_dwordx4 v169, v[64:67], s[100:101] nt
	s_add_u32 s100, s100, 0x4000
	s_addc_u32 s101, s101, 0
	s_waitcnt lgkmcnt(2)
	global_store_dwordx4 v169, v[68:71], s[100:101] nt
	s_add_u32 s100, s100, 0x4000
	s_addc_u32 s101, s101, 0
	s_waitcnt lgkmcnt(1)
	global_store_dwordx4 v169, v[72:75], s[100:101] nt
	s_add_u32 s100, s100, 0x4000
	s_addc_u32 s101, s101, 0
	s_waitcnt lgkmcnt(0)
	global_store_dwordx4 v169, v[76:79], s[100:101] nt
	s_add_u32 s100, s100, 0x4000
	s_addc_u32 s101, s101, 0
	s_branch .Lof1_d

.LBB0_942:
	v_readlane_b32 vcc_lo, v253, 47
	v_readlane_b32 vcc_hi, v253, 48
	s_nop 1
	s_and_b64 vcc, exec, vcc
	s_cbranch_scc0 .Lof2_h
	v_lshrrev_b32_e32 v48, 6, v250
	v_mul_u32_u24_e32 v48, 0x2200, v48
	v_lshrrev_b32_e32 v49, 4, v225
	v_mul_u32_u24_e32 v49, 0x110, v49
	v_and_b32_e32 v50, 15, v225
	v_lshl_add_u32 v49, v50, 4, v49
	v_add_u32_e32 v48, v48, v49
	v_add_u32_e32 v48, 0x1000, v48
	ds_read_b128 v[32:35], v48
	ds_read_b128 v[36:39], v48 offset:1088
	ds_read_b128 v[40:43], v48 offset:2176
	ds_read_b128 v[44:47], v48 offset:3264
	s_waitcnt lgkmcnt(3)
	global_store_dwordx4 v169, v[32:35], s[100:101] nt
	s_add_u32 s100, s100, 0x4000
	s_addc_u32 s101, s101, 0
	s_waitcnt lgkmcnt(2)
	global_store_dwordx4 v169, v[36:39], s[100:101] nt
	s_add_u32 s100, s100, 0x4000
	s_addc_u32 s101, s101, 0
	s_waitcnt lgkmcnt(1)
	global_store_dwordx4 v169, v[40:43], s[100:101] nt
	s_add_u32 s100, s100, 0x4000
	s_addc_u32 s101, s101, 0
	s_waitcnt lgkmcnt(0)
	global_store_dwordx4 v169, v[44:47], s[100:101] nt
	s_add_u32 s100, s100, 0x4000
	s_addc_u32 s101, s101, 0
	ds_read_b128 v[32:35], v48 offset:4352
	ds_read_b128 v[36:39], v48 offset:5440
	ds_read_b128 v[40:43], v48 offset:6528
	ds_read_b128 v[44:47], v48 offset:7616
	s_waitcnt lgkmcnt(3)
	global_store_dwordx4 v169, v[32:35], s[100:101] nt
	s_add_u32 s100, s100, 0x4000
	s_addc_u32 s101, s101, 0
	s_waitcnt lgkmcnt(2)
	global_store_dwordx4 v169, v[36:39], s[100:101] nt
	s_add_u32 s100, s100, 0x4000
	s_addc_u32 s101, s101, 0
	s_waitcnt lgkmcnt(1)
	global_store_dwordx4 v169, v[40:43], s[100:101] nt
	s_add_u32 s100, s100, 0x4000
	s_addc_u32 s101, s101, 0
	s_waitcnt lgkmcnt(0)
	global_store_dwordx4 v169, v[44:47], s[100:101] nt
	s_add_u32 s100, s100, 0x4000
	s_addc_u32 s101, s101, 0
	s_branch .Lof2_d

.LBB0_974:
	v_readlane_b32 vcc_lo, v253, 47
	v_readlane_b32 vcc_hi, v253, 48
	s_nop 1
	s_and_b64 vcc, exec, vcc
	s_cbranch_scc0 .Lof3_h
	v_lshrrev_b32_e32 v16, 6, v250
	v_mul_u32_u24_e32 v16, 0x2200, v16
	v_lshrrev_b32_e32 v17, 4, v225
	v_mul_u32_u24_e32 v17, 0x110, v17
	v_and_b32_e32 v18, 15, v225
	v_lshl_add_u32 v17, v18, 4, v17
	v_add_u32_e32 v16, v16, v17
	v_add_u32_e32 v16, 0x1000, v16
	ds_read_b128 v[0:3], v16
	ds_read_b128 v[4:7], v16 offset:1088
	ds_read_b128 v[8:11], v16 offset:2176
	ds_read_b128 v[12:15], v16 offset:3264
	s_waitcnt lgkmcnt(3)
	global_store_dwordx4 v169, v[0:3], s[100:101] nt
	s_add_u32 s100, s100, 0x4000
	s_addc_u32 s101, s101, 0
	s_waitcnt lgkmcnt(2)
	global_store_dwordx4 v169, v[4:7], s[100:101] nt
	s_add_u32 s100, s100, 0x4000
	s_addc_u32 s101, s101, 0
	s_waitcnt lgkmcnt(1)
	global_store_dwordx4 v169, v[8:11], s[100:101] nt
	s_add_u32 s100, s100, 0x4000
	s_addc_u32 s101, s101, 0
	s_waitcnt lgkmcnt(0)
	global_store_dwordx4 v169, v[12:15], s[100:101] nt
	s_add_u32 s100, s100, 0x4000
	s_addc_u32 s101, s101, 0
	ds_read_b128 v[0:3], v16 offset:4352
	ds_read_b128 v[4:7], v16 offset:5440
	ds_read_b128 v[8:11], v16 offset:6528
	ds_read_b128 v[12:15], v16 offset:7616
	s_waitcnt lgkmcnt(3)
	global_store_dwordx4 v169, v[0:3], s[100:101] nt
	s_add_u32 s100, s100, 0x4000
	s_addc_u32 s101, s101, 0
	s_waitcnt lgkmcnt(2)
	global_store_dwordx4 v169, v[4:7], s[100:101] nt
	s_add_u32 s100, s100, 0x4000
	s_addc_u32 s101, s101, 0
	s_waitcnt lgkmcnt(1)
	global_store_dwordx4 v169, v[8:11], s[100:101] nt
	s_add_u32 s100, s100, 0x4000
	s_addc_u32 s101, s101, 0
	s_waitcnt lgkmcnt(0)
	global_store_dwordx4 v169, v[12:15], s[100:101] nt
	s_add_u32 s100, s100, 0x4000
	s_addc_u32 s101, s101, 0
	s_branch .Lof3_d
